# HGRN chain loop: prefetch no longer drained by a stray vmcnt(0) in phase a; loop-head wait leaves the 4 output stores in flight
# speedup vs baseline: 1.0429x; 1.0006x over previous
; DI int opaque_tid() { int t = threadIdx.x; asm volatile("" : "+v"(t)); return t; }
; DI void hgrn_item(const Params& p, const int ch) {
;     ...
;   int hh, dir, S, T0;
;   if (ch < 16) { hh = (ch >> 1) & 3; dir = ch & 1; S = 16384; T0 = 32768 + (ch >> 3) * 16384; }
;   else { const int cc = ch - 16; hh = (cc >> 1) & 3; dir = cc & 1; S = 8192; T0 = (cc >> 3) * 8192; }
;   const int tid = opaque_tid(), wid = __builtin_amdgcn_readfirstlane(tid >> 6), lane = tid & 63, l15 = lane & 15, fq = lane >> 4;
;   const int kp = tid & 63, seg = wid, k0 = 2 * kp;
;   const int N = S >> 6;
;   const int cstart = dir ? 8 * seg + 7 : 8 * seg, cstep = dir ? -1 : 1;
;   const unsigned* Fg = (const unsigned*)((const bf16_t*)(p.ws + (dir ? WS_FBW : WS_FFW)) + (size_t)T0 * 512 + hh * 128) + kp;
;   const unsigned* Qg = (const unsigned*)((const bf16_t*)(p.ws + WS_QH) + (size_t)T0 * 512 + hh * 128) + kp;
;   const bf16_t* Vg = (const bf16_t*)(p.ws + WS_IHT) + (size_t)T0 * 512 + (size_t)(hh * 128) * S;
;   bf16_t* Od = (bf16_t*)p.out + (size_t)dir * NTOK * 512 + (size_t)T0 * 512 + hh * 128 + wid * 16 + fq * 4;
;   f32x4 St[8];
; #pragma unroll
;   for (int i = 0; i < 8; ++i) St[i] = (f32x4){0.f, 0.f, 0.f, 0.f};
;   unsigned fraw[8], qraw[8];
;   const char* vsrc[2];
; #pragma unroll
;   for (int i = 0; i < 2; ++i) { const int R = 8 * (2 * wid + i) + (lane >> 3), g = (lane & 7) ^ ((R >> 1) & 7); vsrc[i] = (const char*)(Vg + (size_t)R * S) + g * 16; }
;     ...
;   __syncthreads();
;   HG_LOAD(dir ? N - 1 : 0, 0);
.LBB0_1000:
	s_and_b64 vcc, exec, s[0:1]
	s_cbranch_vccz .LBB0_952
	v_mov_b32_e32 v16, v202
	s_and_b32 s9, s12, 1
	v_readfirstlane_b32 s3, v16
	s_ashr_i32 s8, s3, 6
	s_cmp_lt_i32 s8, 6
	s_cselect_b64 s[0:1], -1, 0
	s_cmp_lt_i32 s8, 7
	s_cselect_b64 s[4:5], -1, 0
	s_cmp_gt_i32 s8, 7
	s_cselect_b64 s[6:7], -1, 0
	s_cmp_eq_u32 s9, 0
	s_cselect_b64 vcc, -1, 0
	s_cmp_gt_i32 s8, 6
	v_cndmask_b32_e64 v0, 0, 1, s[4:5]
	v_cndmask_b32_e64 v1, 0, 1, s[6:7]
	s_cselect_b64 s[4:5], -1, 0
	s_cmp_eq_u32 s9, 0
	v_cndmask_b32_e32 v17, v0, v1, vcc
	s_cselect_b64 vcc, -1, 0
	s_cmp_lt_i32 s8, 5
	v_cndmask_b32_e64 v0, 0, 1, s[0:1]
	s_cselect_b64 s[0:1], -1, 0
	s_cmp_gt_i32 s8, 5
	v_cndmask_b32_e64 v1, 0, 1, s[4:5]
	s_cselect_b64 s[4:5], -1, 0
	s_cmp_eq_u32 s9, 0
	v_cndmask_b32_e32 v18, v0, v1, vcc
	s_cselect_b64 vcc, -1, 0
	s_cmp_lt_i32 s8, 4
	v_cndmask_b32_e64 v0, 0, 1, s[0:1]
	s_cselect_b64 s[0:1], -1, 0
	s_cmp_gt_i32 s8, 4
	v_cndmask_b32_e64 v1, 0, 1, s[4:5]
	s_cselect_b64 s[4:5], -1, 0
	s_cmp_eq_u32 s9, 0
	v_cndmask_b32_e32 v19, v0, v1, vcc
	s_cselect_b64 vcc, -1, 0
	s_cmp_lt_i32 s8, 3
	v_cndmask_b32_e64 v0, 0, 1, s[0:1]
	s_cselect_b64 s[0:1], -1, 0
	s_cmp_gt_i32 s8, 3
	v_cndmask_b32_e64 v1, 0, 1, s[4:5]
	s_cselect_b64 s[4:5], -1, 0
	s_cmp_eq_u32 s9, 0
	v_cndmask_b32_e32 v20, v0, v1, vcc
	s_cselect_b64 vcc, -1, 0
	s_cmp_lt_i32 s8, 2
	v_cndmask_b32_e64 v0, 0, 1, s[0:1]
	s_cselect_b64 s[0:1], -1, 0
	s_cmp_gt_i32 s8, 2
	v_cndmask_b32_e64 v1, 0, 1, s[4:5]
	s_cselect_b64 s[4:5], -1, 0
	s_cmp_eq_u32 s9, 0
	v_cndmask_b32_e32 v21, v0, v1, vcc
	s_cselect_b64 vcc, -1, 0
	s_cmp_lt_i32 s8, 1
	v_cndmask_b32_e64 v0, 0, 1, s[0:1]
	s_cselect_b64 s[0:1], -1, 0
	s_cmp_gt_i32 s8, 1
	v_cndmask_b32_e64 v1, 0, 1, s[4:5]
	s_cselect_b64 s[4:5], -1, 0
	s_cmp_eq_u32 s9, 0
	v_cndmask_b32_e32 v22, v0, v1, vcc
	s_cselect_b64 vcc, -1, 0
	s_cmp_gt_i32 s8, 0
	v_cndmask_b32_e64 v0, 0, 1, s[0:1]
	v_cndmask_b32_e64 v1, 0, 1, s[4:5]
	s_cselect_b64 s[0:1], -1, 0
	s_lshr_b32 s4, s3, 31
	s_cmp_eq_u32 s9, 0
	v_cndmask_b32_e32 v23, v0, v1, vcc
	s_cselect_b64 vcc, -1, 0
	s_lshl_b32 s6, s8, 3
	s_or_b32 s7, s6, 7
	s_cmp_eq_u32 s9, 0
	v_mov_b32_e32 v1, s4
	s_cselect_b64 s[4:5], -1, 0
	v_cndmask_b32_e64 v0, 0, 1, s[0:1]
	s_and_b64 s[0:1], s[4:5], exec
	s_mov_b32 s0, 0x1a000000
	s_cselect_b32 s48, 1, -1
	s_cselect_b32 s14, s0, 0x1e000000
	s_cselect_b32 s78, s6, s7
	s_cmp_lt_i32 s12, 16
	s_cselect_b32 s0, 11, 10
	s_movk_i32 s6, 0xc000
	s_movk_i32 s7, 0x100
	s_cselect_b32 s1, s6, 0x7fffe000
	s_cselect_b32 s6, 0x8000, s6
	s_cselect_b32 s86, s7, 0x80
	s_cselect_b32 s16, 14, 13
	s_lshl_b32 s0, s12, s0
	s_and_b32 s0, s0, s1
	s_add_i32 s0, s0, s6
	s_ashr_i32 s1, s0, 31
	s_lshl_b32 s6, s12, 6
	s_bfe_i32 s17, s12, 0x10000
	s_and_b32 s70, s6, 0x180
	s_lshl_b64 s[6:7], s[0:1], 10
	s_add_u32 s0, s91, s6
	s_addc_u32 s1, s92, s7
	s_lshl_b32 s18, s70, 1
	s_add_u32 s10, s0, s18
	s_addc_u32 s11, s1, 0
	s_lshl_b64 s[12:13], s[70:71], s16
	s_lshl_b32 s0, s9, 26
	s_add_u32 s0, s56, s0
	s_addc_u32 s1, s57, 0
	s_add_u32 s9, s0, s6
	s_addc_u32 s19, s1, s7
	s_lshl_b32 s0, s8, 4
	s_ashr_i32 s1, s0, 31
	s_add_u32 s14, s58, s14
	s_addc_u32 s15, s59, 0
	s_add_u32 s14, s14, s6
	s_addc_u32 s15, s15, s7
	v_and_b32_e32 v25, 63, v16
	s_add_u32 s14, s14, s18
	s_addc_u32 s15, s15, 0
	v_lshlrev_b32_e32 v192, 2, v25
	v_lshl_add_u64 v[56:57], s[14:15], 0, v[192:193]
	s_add_u32 s14, s93, s6
	v_bfe_u32 v4, v16, 3, 3
	v_cndmask_b32_e32 v24, v1, v0, vcc
	s_addc_u32 s15, s94, s7
	s_lshl_b64 s[6:7], s[12:13], 1
	v_or_b32_e32 v0, s0, v4
	s_add_u32 s6, s14, s6
	v_ashrrev_i32_e32 v1, 31, v0
	s_addc_u32 s7, s15, s7
	v_lshlrev_b64 v[0:1], s16, v[0:1]
	v_lshlrev_b32_e32 v2, 4, v16
	v_and_b32_e32 v28, 48, v16
	s_movk_i32 s12, 0x70
	v_lshl_add_u64 v[0:1], v[0:1], 1, s[6:7]
	v_bitop3_b32 v2, v2, v28, s12 bitop3:0x6c
	v_mov_b32_e32 v3, v193
	v_lshl_add_u64 v[58:59], v[0:1], 0, v[2:3]
	v_or_b32_e32 v1, 8, v4
	v_or_b32_e32 v0, s0, v1
	v_lshrrev_b32_e32 v1, 1, v1
	v_xor_b32_e32 v2, v1, v16
	v_ashrrev_i32_e32 v1, 31, v0
	v_lshlrev_b64 v[0:1], s16, v[0:1]
	s_add_u32 s9, s9, s18
	v_lshl_add_u64 v[0:1], v[0:1], 1, s[6:7]
	v_lshl_add_u64 v[62:63], s[10:11], 0, v[192:193]
	s_addc_u32 s10, s19, 0
	s_lshl_b64 s[6:7], s[0:1], 1
	s_add_u32 s6, s9, s6
	s_addc_u32 s7, s10, s7
	s_add_i32 s41, s86, -1
	s_lshl_b32 s1, s41, 6
	s_and_b32 s1, s17, s1
	s_add_i32 s10, s78, s1
	s_ashr_i32 s11, s10, 31
	v_lshlrev_b32_e32 v2, 4, v2
	s_lshl_b64 s[12:13], s[10:11], 10
	s_add_i32 s10, s10, s48
	v_and_b32_e32 v2, 0x70, v2
	s_ashr_i32 s11, s10, 31
	v_lshl_add_u64 v[60:61], v[0:1], 0, v[2:3]
	v_lshl_add_u64 v[0:1], v[56:57], 0, s[12:13]
	v_lshl_add_u64 v[2:3], v[62:63], 0, s[12:13]
	s_lshl_b64 s[12:13], s[10:11], 10
	s_add_i32 s10, s10, s48
	s_ashr_i32 s11, s10, 31
	v_lshl_add_u64 v[4:5], v[56:57], 0, s[12:13]
	v_lshl_add_u64 v[6:7], v[62:63], 0, s[12:13]
	s_lshl_b64 s[12:13], s[10:11], 10
	s_add_i32 s10, s10, s48
	s_ashr_i32 s11, s10, 31
	v_lshl_add_u64 v[8:9], v[56:57], 0, s[12:13]
	v_lshl_add_u64 v[10:11], v[62:63], 0, s[12:13]
	s_lshl_b64 s[12:13], s[10:11], 10
	s_add_i32 s10, s10, s48
	s_ashr_i32 s11, s10, 31
	v_lshl_add_u64 v[12:13], v[56:57], 0, s[12:13]
	v_lshl_add_u64 v[14:15], v[62:63], 0, s[12:13]
	s_lshl_b64 s[12:13], s[10:11], 10
	s_add_i32 s10, s10, s48
	s_ashr_i32 s11, s10, 31
	s_barrier
; DI void hgrn_item(const Params& p, const int ch) {
;     ...
; #pragma unroll
;   for (int i = 0; i < 8; ++i) St[i] = (f32x4){0.f, 0.f, 0.f, 0.f};
;   unsigned fraw[8], qraw[8];
;   const char* vsrc[2];
; #pragma unroll
;   for (int i = 0; i < 2; ++i) { const int R = 8 * (2 * wid + i) + (lane >> 3), g = (lane & 7) ^ ((R >> 1) & 7); vsrc[i] = (const char*)(Vg + (size_t)R * S) + g * 16; }
;     ...
;   __syncthreads();
;   HG_LOAD(dir ? N - 1 : 0, 0);
;   const int vrd = (16 * wid + l15) * 128;
;   const int swv = (l15 >> 1) & 7;
	global_load_dword v74, v[0:1], off
	global_load_dword v75, v[2:3], off
	global_load_dword v76, v[4:5], off
	global_load_dword v77, v[6:7], off
	global_load_dword v78, v[8:9], off
	global_load_dword v79, v[10:11], off
	global_load_dword v80, v[12:13], off
	global_load_dword v87, v[14:15], off
	v_lshl_add_u64 v[0:1], v[56:57], 0, s[12:13]
	v_lshl_add_u64 v[2:3], v[62:63], 0, s[12:13]
	s_lshl_b64 s[12:13], s[10:11], 10
	s_add_i32 s10, s10, s48
	s_ashr_i32 s11, s10, 31
	v_lshl_add_u64 v[4:5], v[56:57], 0, s[12:13]
	v_lshl_add_u64 v[6:7], v[62:63], 0, s[12:13]
	s_lshl_b64 s[12:13], s[10:11], 10
	s_add_i32 s10, s10, s48
	s_ashr_i32 s11, s10, 31
	s_lshl_b64 s[10:11], s[10:11], 10
	v_lshl_add_u64 v[8:9], v[56:57], 0, s[12:13]
	v_lshl_add_u64 v[10:11], v[62:63], 0, s[12:13]
	v_lshl_add_u64 v[12:13], v[56:57], 0, s[10:11]
	v_lshl_add_u64 v[14:15], v[62:63], 0, s[10:11]
	global_load_dword v88, v[0:1], off
	global_load_dword v89, v[2:3], off
	global_load_dword v90, v[4:5], off
	global_load_dword v91, v[6:7], off
	global_load_dword v92, v[8:9], off
	global_load_dword v93, v[10:11], off
	global_load_dword v94, v[12:13], off
	global_load_dword v103, v[14:15], off
	s_lshl_b32 s70, s1, 1
	s_lshl_b32 s1, s8, 11
	s_add_i32 s1, s97, s1
	v_lshl_add_u64 v[0:1], v[58:59], 0, s[70:71]
	s_mov_b32 m0, s1
	v_bfe_u32 v26, v16, 4, 2
	global_load_lds_dwordx4 v[0:1], off
	v_lshl_add_u64 v[0:1], v[60:61], 0, s[70:71]
	s_add_i32 m0, s1, 0x400
	v_lshlrev_b32_e32 v72, 3, v25
	global_load_lds_dwordx4 v[0:1], off
	v_lshlrev_b32_e32 v0, 3, v26
	v_mov_b32_e32 v1, v193
	v_lshl_add_u64 v[64:65], s[6:7], 0, v[0:1]
	s_lshl_b32 s6, s8, 9
	s_add_i32 s70, s6, 0
	v_add_u32_e32 v81, 0, v72
	s_cmp_lt_u32 s3, 64
	v_sub_u32_e32 v83, v81, v192
	s_movk_i32 s6, 0x11c
	s_cselect_b64 s[64:65], -1, 0
	s_ashr_i32 s3, s3, 3
	v_mad_u32_u24 v84, v25, s6, v83
	v_bfi_b32 v4, -16, s3, v16
	s_movk_i32 s6, 0x110
	v_and_b32_e32 v7, 1, v24
	v_mul_lo_u32 v4, v4, s6
	v_cmp_eq_u32_e64 s[6:7], 1, v7
	v_and_b32_e32 v7, 1, v23
	s_lshl_b32 s22, s8, 5
	v_cmp_eq_u32_e64 s[8:9], 1, v7
	v_and_b32_e32 v7, 1, v22
	v_cmp_eq_u32_e64 s[10:11], 1, v7
	v_and_b32_e32 v7, 1, v21
	v_cmp_eq_u32_e64 s[12:13], 1, v7
	v_and_b32_e32 v7, 1, v20
	v_cmp_eq_u32_e64 s[14:15], 1, v7
	v_and_b32_e32 v7, 1, v19
	v_cmp_eq_u32_e64 s[16:17], 1, v7
	v_and_b32_e32 v7, 1, v18
	v_lshlrev_b32_e32 v27, 2, v26
	v_and_b32_e32 v73, 15, v16
	v_cmp_eq_u32_e64 s[18:19], 1, v7
	v_and_b32_e32 v7, 1, v17
	v_add_u32_e32 v5, 0, v4
	v_and_or_b32 v4, s3, -16, v27
	v_cmp_eq_u32_e64 s[20:21], 1, v7
	s_add_i32 s23, s78, s48
	v_and_or_b32 v7, s22, 32, v73
	s_mul_i32 s3, s23, 0x110
	s_add_i32 s23, s23, s48
	v_cmp_le_i32_e32 vcc, v4, v7
	s_mul_i32 s33, s23, 0x110
	s_add_i32 s23, s23, s48
	v_cndmask_b32_e64 v9, 0, 1, vcc
	v_cmp_ge_i32_e32 vcc, v4, v7
	s_mul_i32 s49, s23, 0x110
	s_add_i32 s23, s23, s48
	v_cndmask_b32_e64 v10, 0, 1, vcc
	s_mul_i32 s52, s23, 0x110
	s_add_i32 s23, s23, s48
	v_cndmask_b32_e64 v9, v10, v9, s[4:5]
	s_mul_i32 s90, s23, 0x110
	s_add_i32 s23, s23, s48
	v_and_b32_e32 v9, 1, v9
	s_mul_i32 s79, s23, 0x110
	s_add_i32 s44, s23, s48
	v_cmp_eq_u32_e64 s[22:23], 1, v9
	v_or_b32_e32 v9, 1, v4
	v_cmp_lt_i32_e32 vcc, v4, v7
	v_mul_u32_u24_e32 v8, 0x110, v7
	v_lshl_add_u32 v6, v4, 1, 0
	v_cndmask_b32_e64 v10, 0, 1, vcc
	v_cmp_ge_i32_e32 vcc, v9, v7
	v_lshrrev_b32_e32 v2, 1, v16
	v_bfe_u32 v3, v16, 1, 3
	v_cndmask_b32_e64 v11, 0, 1, vcc
	v_cndmask_b32_e64 v10, v11, v10, s[4:5]
	v_and_b32_e32 v10, 1, v10
	v_cmp_eq_u32_e64 s[24:25], 1, v10
	v_or_b32_e32 v10, 2, v4
	v_cmp_le_i32_e32 vcc, v10, v7
	v_bitop3_b32 v2, v26, v2, 7 bitop3:0x78
	v_or_b32_e32 v1, s0, v73
	v_cndmask_b32_e64 v11, 0, 1, vcc
	v_cmp_ge_i32_e32 vcc, v10, v7
	v_lshlrev_b32_e32 v95, 4, v2
	v_bitop3_b32 v2, v26, v3, 4 bitop3:0x36
	v_cndmask_b32_e64 v12, 0, 1, vcc
	v_cndmask_b32_e64 v11, v12, v11, s[4:5]
	v_and_b32_e32 v11, 1, v11
	v_cmp_eq_u32_e64 s[26:27], 1, v11
	v_or_b32_e32 v11, 3, v4
	v_cmp_le_i32_e32 vcc, v11, v7
	v_lshl_add_u32 v85, v1, 7, s97
	v_mul_i32_i24_e32 v1, 0xfffffee8, v25
	v_cndmask_b32_e64 v12, 0, 1, vcc
	v_cmp_ge_i32_e32 vcc, v11, v7
	v_add_u32_e32 v86, 0, v28
	v_add_u32_e32 v0, 0, v0
	v_cndmask_b32_e64 v13, 0, 1, vcc
	v_cndmask_b32_e64 v12, v13, v12, s[4:5]
	v_and_b32_e32 v12, 1, v12
	v_cmp_eq_u32_e64 s[28:29], 1, v12
	v_mul_u32_u24_e32 v12, 0x90, v7
	v_or_b32_e32 v7, 16, v7
	v_cmp_le_i32_e32 vcc, v4, v7
	v_lshlrev_b32_e32 v96, 4, v2
	v_mul_u32_u24_e32 v2, 0x90, v73
	v_cndmask_b32_e64 v13, 0, 1, vcc
	v_cmp_ge_i32_e32 vcc, v4, v7
	v_mul_u32_u24_e32 v3, 0x110, v73
	s_mov_b32 s80, 1
	v_cndmask_b32_e64 v14, 0, 1, vcc
	v_cmp_lt_i32_e32 vcc, v4, v7
	v_cndmask_b32_e64 v13, v14, v13, s[4:5]
	v_and_b32_e32 v13, 1, v13
	v_cndmask_b32_e64 v4, 0, 1, vcc
	v_cmp_ge_i32_e32 vcc, v9, v7
	s_mov_b32 s96, 0
	v_add_u32_e32 v82, 0xf600, v81
	v_cndmask_b32_e64 v9, 0, 1, vcc
	v_cndmask_b32_e64 v4, v9, v4, s[4:5]
	v_and_b32_e32 v4, 1, v4
	v_cmp_le_i32_e32 vcc, v10, v7
	v_cmp_eq_u32_e64 s[34:35], 1, v4
	s_mulk_i32 s44, 0x110
	v_cndmask_b32_e64 v4, 0, 1, vcc
	v_cmp_ge_i32_e32 vcc, v10, v7
	v_cmp_eq_u32_e64 s[30:31], 1, v13
	v_add_u32_e32 v97, v84, v1
	v_cndmask_b32_e64 v9, 0, 1, vcc
	v_cndmask_b32_e64 v4, v9, v4, s[4:5]
	v_and_b32_e32 v4, 1, v4
	v_cmp_le_i32_e32 vcc, v11, v7
	v_cmp_eq_u32_e64 s[36:37], 1, v4
	v_add_u32_e32 v98, v5, v28
	v_cndmask_b32_e64 v4, 0, 1, vcc
	v_cmp_ge_i32_e32 vcc, v11, v7
	v_add_u32_e32 v99, v86, v8
	v_add_u32_e32 v100, v6, v12
	v_cndmask_b32_e64 v7, 0, 1, vcc
	v_cndmask_b32_e64 v4, v7, v4, s[4:5]
	v_and_b32_e32 v4, 1, v4
	v_cmp_eq_u32_e64 s[38:39], 1, v4
	v_mov_b32_e32 v4, 0
	v_add_u32_e32 v101, v86, v2
	v_add_u32_e32 v102, v0, v3
	v_mov_b32_e32 v5, v4
	v_mov_b32_e32 v6, v4
	v_mov_b32_e32 v7, v4
	v_mov_b32_e32 v0, v4
	v_mov_b32_e32 v1, v4
	v_mov_b32_e32 v2, v4
	v_mov_b32_e32 v3, v4
	v_mov_b32_e32 v12, v4
	v_mov_b32_e32 v13, v4
	v_mov_b32_e32 v14, v4
	v_mov_b32_e32 v15, v4
	v_mov_b32_e32 v8, v4
	v_mov_b32_e32 v9, v4
	v_mov_b32_e32 v10, v4
	v_mov_b32_e32 v11, v4
	v_mov_b32_e32 v20, v4
	v_mov_b32_e32 v21, v4
	v_mov_b32_e32 v22, v4
	v_mov_b32_e32 v23, v4
	v_mov_b32_e32 v16, v4
	v_mov_b32_e32 v17, v4
	v_mov_b32_e32 v18, v4
	v_mov_b32_e32 v19, v4
	v_mov_b32_e32 v24, v4
	v_mov_b32_e32 v25, v4
	v_mov_b32_e32 v26, v4
	v_mov_b32_e32 v27, v4
	v_mov_b32_e32 v28, v4
	v_mov_b32_e32 v29, v4
	v_mov_b32_e32 v30, v4
	v_mov_b32_e32 v31, v4
	s_waitcnt vmcnt(0)
	s_branch .Lhg_after_wait
; DI void hgrn_item(const Params& p, const int ch) {
;     ...
;     {
;       const int sb = wid >> 1;
; #pragma unroll
;       for (int cbi = 0; cbi < 2; ++cbi) {
;         const int cb = (wid & 1) * 2 + cbi;
;         f32x4 acc = (f32x4){0.f, 0.f, 0.f, 0.f};
; #pragma unroll
;         for (int ks = 0; ks < 4; ++ks) {
;           const bf16x8 A = *(const LAS bf16x8*)(lds + HG_KT + (16 * sb + l15) * 272 + ks * 64 + fq * 16);
;           const bf16x8 B = *(const LAS bf16x8*)(lds + HG_QT + (16 * cb + l15) * 272 + ks * 64 + fq * 16);
;           acc = MFMA16(A, B, acc);
;         }
;         const int s0 = 16 * sb + 4 * fq, cc = 16 * cb + l15;
;         float m[4];
; #pragma unroll
;         for (int e = 0; e < 4; ++e) { const bool keep = dir ? (s0 + e >= cc) : (s0 + e <= cc); m[e] = keep ? acc[e] : 0.f; }
;         uint2 q; q.x = pk_bf16(m[0], m[1]); q.y = pk_bf16(m[2], m[3]);
;         *(uint2*)(shm_raw + HG_AM + cc * 144 + s0 * 2) = q;
;       }
;     }
;     __syncthreads();
;     bf16x8 vf[2];
; #pragma unroll
;     for (int st = 0; st < 2; ++st) vf[st] = *(const LAS bf16x8*)(lds + HG_VT + (it & 1) * 16384 + vrd + (((4 * st + fq) ^ swv) << 4));
;     bf16x8 Sb[4];
; #pragma unroll
;     for (int m = 0; m < 4; ++m) {
;       u32x4 pk;
;       pk[0] = pk_bf16(St[2 * m][0], St[2 * m][1]); pk[1] = pk_bf16(St[2 * m][2], St[2 * m][3]);
;       pk[2] = pk_bf16(St[2 * m + 1][0], St[2 * m + 1][1]); pk[3] = pk_bf16(St[2 * m + 1][2], St[2 * m + 1][3]);
;       Sb[m] = __builtin_bit_cast(bf16x8, pk);
;     }
; #pragma unroll
;     for (int cb = 0; cb < 4; ++cb) {
;       f32x4 acc = (f32x4){0.f, 0.f, 0.f, 0.f};
; #pragma unroll
;       for (int st = 0; st < 2; ++st) {
;         const bf16x8 B = *(const LAS bf16x8*)(lds + HG_AM + (16 * cb + l15) * 144 + st * 64 + fq * 16);
;         acc = MFMA16(vf[st], B, acc);
;       }
; #pragma unroll
;       for (int m = 0; m < 4; ++m) {
;         const s16x4 lo = *(const LAS s16x4*)(lds + HG_QT + (16 * cb + l15) * 272 + (32 * m + 4 * fq) * 2);
;         const s16x4 hi = *(const LAS s16x4*)(lds + HG_QT + (16 * cb + l15) * 272 + (32 * m + 16 + 4 * fq) * 2);
;         const bf16x8 B = __builtin_shufflevector(lo, hi, 0, 1, 2, 3, 4, 5, 6, 7);
;         acc = MFMA16(Sb[m], B, acc);
;       }
;       uint2 o; o.x = pk_bf16(acc[0], acc[1]); o.y = pk_bf16(acc[2], acc[3]);
;       *(uint2*)(Od + (size_t)(t0 + 16 * cb + l15) * 512) = o;
.LBB0_1002:
	ds_read_b128 v[32:35], v98 offset:17408
	ds_read_b128 v[36:39], v99
	s_add_i32 s84, s80, -1
	s_and_b64 s[42:43], s[4:5], exec
	s_cselect_b32 s41, s84, s41
	s_and_b32 s42, s96, 0x4000
	s_waitcnt lgkmcnt(0)
	v_mfma_f32_16x16x32_bf16 v[32:35], v[32:35], v[36:39], 0
	ds_read_b128 v[36:39], v98 offset:17472
	ds_read_b128 v[40:43], v99 offset:64
	v_cvt_pk_bf16_f32 v52, v4, v5
	v_cvt_pk_bf16_f32 v53, v6, v7
	v_cvt_pk_bf16_f32 v54, v0, v1
	s_waitcnt lgkmcnt(0)
	v_mfma_f32_16x16x32_bf16 v[32:35], v[36:39], v[40:43], v[32:35]
	ds_read_b128 v[36:39], v98 offset:17536
	ds_read_b128 v[40:43], v99 offset:128
	v_cvt_pk_bf16_f32 v55, v2, v3
	v_cvt_pk_bf16_f32 v48, v12, v13
	s_waitcnt lgkmcnt(0)
	v_mfma_f32_16x16x32_bf16 v[32:35], v[36:39], v[40:43], v[32:35]
	ds_read_b128 v[36:39], v98 offset:17600
	ds_read_b128 v[40:43], v99 offset:192
	v_cvt_pk_bf16_f32 v49, v14, v15
	v_cvt_pk_bf16_f32 v50, v8, v9
	s_waitcnt lgkmcnt(0)
	v_mfma_f32_16x16x32_bf16 v[32:35], v[36:39], v[40:43], v[32:35]
	v_cvt_pk_bf16_f32 v51, v10, v11
	v_cvt_pk_bf16_f32 v44, v20, v21
	v_cvt_pk_bf16_f32 v45, v22, v23
	s_nop 4
	v_cndmask_b32_e64 v32, 0, v32, s[22:23]
	v_cndmask_b32_e64 v33, 0, v33, s[24:25]
	v_cndmask_b32_e64 v34, 0, v34, s[26:27]
	v_cndmask_b32_e64 v35, 0, v35, s[28:29]
	v_cvt_pk_bf16_f32 v32, v32, v33
	v_cvt_pk_bf16_f32 v33, v34, v35
	ds_write_b64 v100, v[32:33] offset:53248
	ds_read_b128 v[32:35], v98 offset:17408
	ds_read_b128 v[36:39], v99 offset:4352
	s_waitcnt lgkmcnt(0)
	v_mfma_f32_16x16x32_bf16 v[32:35], v[32:35], v[36:39], 0
	ds_read_b128 v[36:39], v98 offset:17472
	ds_read_b128 v[40:43], v99 offset:4416
	v_cvt_pk_bf16_f32 v46, v16, v17
	v_cvt_pk_bf16_f32 v47, v18, v19
	s_waitcnt lgkmcnt(0)
	v_mfma_f32_16x16x32_bf16 v[32:35], v[36:39], v[40:43], v[32:35]
	ds_read_b128 v[36:39], v98 offset:17536
	ds_read_b128 v[40:43], v99 offset:4480
	v_lshl_or_b32 v66, s41, 6, v73
	v_ashrrev_i32_e32 v67, 31, v66
	s_waitcnt lgkmcnt(0)
	v_mfma_f32_16x16x32_bf16 v[32:35], v[36:39], v[40:43], v[32:35]
	ds_read_b128 v[36:39], v98 offset:17600
	ds_read_b128 v[40:43], v99 offset:4544
	s_add_i32 s80, s80, 1
	s_cmp_eq_u32 s45, -1
	s_waitcnt lgkmcnt(0)
	v_mfma_f32_16x16x32_bf16 v[32:35], v[36:39], v[40:43], v[32:35]
	v_cvt_pk_bf16_f32 v40, v24, v25
	v_cvt_pk_bf16_f32 v41, v26, v27
	v_cvt_pk_bf16_f32 v42, v28, v29
	s_nop 4
	v_cndmask_b32_e64 v32, 0, v32, s[30:31]
	v_cndmask_b32_e64 v33, 0, v33, s[34:35]
	v_cndmask_b32_e64 v34, 0, v34, s[36:37]
	v_cndmask_b32_e64 v35, 0, v35, s[38:39]
	v_cvt_pk_bf16_f32 v32, v32, v33
	v_cvt_pk_bf16_f32 v33, v34, v35
	ds_write_b64 v100, v[32:33] offset:55552
	v_add_u32_e32 v32, s42, v85
	v_add_u32_e32 v33, v32, v95
	s_waitcnt lgkmcnt(0)
	s_barrier
	ds_read_b128 v[36:39], v33
	ds_read_b128 v[104:107], v101 offset:53312
	v_add_u32_e32 v32, v32, v96
	ds_read_b128 v[32:35], v32
	ds_read_b128 v[68:71], v101 offset:53248
	s_waitcnt lgkmcnt(0)
	v_mfma_f32_16x16x32_bf16 v[68:71], v[36:39], v[68:71], 0
	v_cvt_pk_bf16_f32 v43, v30, v31
	s_mov_b32 s96, s40
	s_mov_b32 s41, s45
	v_mfma_f32_16x16x32_bf16 v[68:71], v[32:35], v[104:107], v[68:71]
	ds_read2_b64 v[104:107], v102 offset1:4
	s_waitcnt lgkmcnt(0)
	v_mfma_f32_16x16x32_bf16 v[68:71], v[52:55], v[104:107], v[68:71]
	ds_read2_b64 v[104:107], v102 offset0:8 offset1:12
	s_waitcnt lgkmcnt(0)
	v_mfma_f32_16x16x32_bf16 v[68:71], v[48:51], v[104:107], v[68:71]
	ds_read2_b64 v[104:107], v102 offset0:16 offset1:20
	s_waitcnt lgkmcnt(0)
	v_mfma_f32_16x16x32_bf16 v[68:71], v[44:47], v[104:107], v[68:71]
	ds_read2_b64 v[104:107], v102 offset0:24 offset1:28
	s_waitcnt lgkmcnt(0)
	v_mfma_f32_16x16x32_bf16 v[68:71], v[40:43], v[104:107], v[68:71]
	ds_read_b128 v[104:107], v101 offset:55616
	s_nop 6
	v_cvt_pk_bf16_f32 v68, v68, v69
	v_cvt_pk_bf16_f32 v69, v70, v71
	v_lshlrev_b64 v[70:71], 10, v[66:67]
	v_lshl_add_u64 v[70:71], v[64:65], 0, v[70:71]
	global_store_dwordx2 v[70:71], v[68:69], off
	ds_read_b128 v[68:71], v101 offset:55552
	s_waitcnt lgkmcnt(0)
	v_mfma_f32_16x16x32_bf16 v[68:71], v[36:39], v[68:71], 0
	v_add_u32_e32 v67, 0x1000, v102
	v_mfma_f32_16x16x32_bf16 v[68:71], v[32:35], v[104:107], v[68:71]
	ds_read2_b64 v[104:107], v67 offset0:32 offset1:36
	s_waitcnt lgkmcnt(0)
	v_mfma_f32_16x16x32_bf16 v[68:71], v[52:55], v[104:107], v[68:71]
	ds_read2_b64 v[104:107], v67 offset0:40 offset1:44
	s_waitcnt lgkmcnt(0)
	v_mfma_f32_16x16x32_bf16 v[68:71], v[48:51], v[104:107], v[68:71]
	ds_read2_b64 v[104:107], v67 offset0:48 offset1:52
	s_waitcnt lgkmcnt(0)
	v_mfma_f32_16x16x32_bf16 v[68:71], v[44:47], v[104:107], v[68:71]
	ds_read2_b64 v[104:107], v67 offset0:56 offset1:60
	v_add_u32_e32 v67, 0x2000, v102
	s_waitcnt lgkmcnt(0)
	v_mfma_f32_16x16x32_bf16 v[68:71], v[40:43], v[104:107], v[68:71]
	ds_read_b128 v[104:107], v101 offset:57920
	s_nop 6
	v_cvt_pk_bf16_f32 v68, v68, v69
	v_cvt_pk_bf16_f32 v69, v70, v71
	v_or_b32_e32 v70, 16, v66
	v_ashrrev_i32_e32 v71, 31, v70
	v_lshlrev_b64 v[70:71], 10, v[70:71]
	v_lshl_add_u64 v[70:71], v[64:65], 0, v[70:71]
	global_store_dwordx2 v[70:71], v[68:69], off
	ds_read_b128 v[68:71], v101 offset:57856
	s_waitcnt lgkmcnt(0)
	v_mfma_f32_16x16x32_bf16 v[68:71], v[36:39], v[68:71], 0
	v_mfma_f32_16x16x32_bf16 v[68:71], v[32:35], v[104:107], v[68:71]
	ds_read2_b64 v[104:107], v67 offset0:64 offset1:68
	s_waitcnt lgkmcnt(0)
	v_mfma_f32_16x16x32_bf16 v[68:71], v[52:55], v[104:107], v[68:71]
	ds_read2_b64 v[104:107], v67 offset0:72 offset1:76
	s_waitcnt lgkmcnt(0)
	v_mfma_f32_16x16x32_bf16 v[68:71], v[48:51], v[104:107], v[68:71]
	ds_read2_b64 v[104:107], v67 offset0:80 offset1:84
	s_waitcnt lgkmcnt(0)
; #define LAS __attribute__((address_space(3)))
; DI unsigned pk_bf16(float lo, float hi) { f32x2 v = {lo, hi}; return __builtin_bit_cast(unsigned, __builtin_convertvector(v, bf16x2_t)); }
; #define MFMA16(a, b, c) __builtin_amdgcn_mfma_f32_16x16x32_bf16((a), (b), (c), 0, 0, 0)
; DI void hgrn_item(const Params& p, const int ch) {
;     ...
;   for (int it = 0; it < N; ++it) {
;     ...
; #pragma unroll
;       for (int m = 0; m < 4; ++m) {
;         const s16x4 lo = *(const LAS s16x4*)(lds + HG_QT + (16 * cb + l15) * 272 + (32 * m + 4 * fq) * 2);
;         const s16x4 hi = *(const LAS s16x4*)(lds + HG_QT + (16 * cb + l15) * 272 + (32 * m + 16 + 4 * fq) * 2);
;         const bf16x8 B = __builtin_shufflevector(lo, hi, 0, 1, 2, 3, 4, 5, 6, 7);
;         acc = MFMA16(Sb[m], B, acc);
;       }
;       uint2 o; o.x = pk_bf16(acc[0], acc[1]); o.y = pk_bf16(acc[2], acc[3]);
;       *(uint2*)(Od + (size_t)(t0 + 16 * cb + l15) * 512) = o;
;     }
; #pragma unroll
;     for (int kb = 0; kb < 8; ++kb) {
;       const float4 dc = *(const float4*)(shm_raw + HG_DEC + (16 * kb + 4 * fq) * 4);
;       f32x4 s = St[kb];
;       s[0] *= dc.x; s[1] *= dc.y; s[2] *= dc.z; s[3] *= dc.w;
; #pragma unroll
;       for (int st = 0; st < 2; ++st) {
;         const bf16x8 A = *(const LAS bf16x8*)(lds + HG_KST + (16 * kb + l15) * 144 + st * 64 + fq * 16);
;         s = MFMA16(A, vf[st], s);
;       }
;       St[kb] = s;
;     }
;     __syncthreads();
	v_mfma_f32_16x16x32_bf16 v[68:71], v[44:47], v[104:107], v[68:71]
	ds_read2_b64 v[104:107], v67 offset0:88 offset1:92
	v_add_u32_e32 v67, 0x3000, v102
	s_waitcnt lgkmcnt(0)
	v_mfma_f32_16x16x32_bf16 v[68:71], v[40:43], v[104:107], v[68:71]
	ds_read_b128 v[104:107], v101 offset:60224
	s_nop 6
	v_cvt_pk_bf16_f32 v68, v68, v69
	v_cvt_pk_bf16_f32 v69, v70, v71
	v_or_b32_e32 v70, 32, v66
	v_ashrrev_i32_e32 v71, 31, v70
	v_lshlrev_b64 v[70:71], 10, v[70:71]
	v_lshl_add_u64 v[70:71], v[64:65], 0, v[70:71]
	global_store_dwordx2 v[70:71], v[68:69], off
	ds_read_b128 v[68:71], v101 offset:60160
	s_waitcnt lgkmcnt(0)
	v_mfma_f32_16x16x32_bf16 v[68:71], v[36:39], v[68:71], 0
	v_mfma_f32_16x16x32_bf16 v[68:71], v[32:35], v[104:107], v[68:71]
	ds_read2_b64 v[104:107], v67 offset0:96 offset1:100
	s_waitcnt lgkmcnt(0)
	v_mfma_f32_16x16x32_bf16 v[52:55], v[52:55], v[104:107], v[68:71]
	s_nop 4
	ds_read2_b64 v[68:71], v67 offset0:104 offset1:108
	s_waitcnt lgkmcnt(0)
	v_mfma_f32_16x16x32_bf16 v[48:51], v[48:51], v[68:71], v[52:55]
	s_nop 2
	ds_read2_b64 v[52:55], v67 offset0:112 offset1:116
	s_waitcnt lgkmcnt(0)
	v_mfma_f32_16x16x32_bf16 v[44:47], v[44:47], v[52:55], v[48:51]
	s_nop 2
	ds_read2_b64 v[48:51], v67 offset0:120 offset1:124
	s_waitcnt lgkmcnt(0)
	v_mfma_f32_16x16x32_bf16 v[40:43], v[40:43], v[48:51], v[44:47]
	s_nop 7
	v_cvt_pk_bf16_f32 v40, v40, v41
	v_cvt_pk_bf16_f32 v41, v42, v43
	v_or_b32_e32 v42, 48, v66
	v_ashrrev_i32_e32 v43, 31, v42
	v_lshlrev_b64 v[42:43], 10, v[42:43]
	v_lshl_add_u64 v[42:43], v[64:65], 0, v[42:43]
	global_store_dwordx2 v[42:43], v[40:41], off
	ds_read_b128 v[40:43], v86 offset:62464
	s_waitcnt lgkmcnt(0)
	v_pk_mul_f32 v[4:5], v[4:5], v[40:41]
	v_pk_mul_f32 v[6:7], v[6:7], v[42:43]
	ds_read_b128 v[40:43], v101 offset:34816
	s_waitcnt lgkmcnt(0)
	v_mfma_f32_16x16x32_bf16 v[4:7], v[40:43], v[36:39], v[4:7]
	ds_read_b128 v[40:43], v101 offset:34880
	s_waitcnt lgkmcnt(0)
	v_mfma_f32_16x16x32_bf16 v[4:7], v[40:43], v[32:35], v[4:7]
	ds_read_b128 v[40:43], v86 offset:62528
	s_waitcnt lgkmcnt(0)
	v_pk_mul_f32 v[0:1], v[0:1], v[40:41]
	v_pk_mul_f32 v[2:3], v[2:3], v[42:43]
	ds_read_b128 v[40:43], v101 offset:37120
	s_waitcnt lgkmcnt(0)
	v_mfma_f32_16x16x32_bf16 v[0:3], v[40:43], v[36:39], v[0:3]
	ds_read_b128 v[40:43], v101 offset:37184
	s_waitcnt lgkmcnt(0)
	v_mfma_f32_16x16x32_bf16 v[0:3], v[40:43], v[32:35], v[0:3]
	ds_read_b128 v[40:43], v86 offset:62592
	s_waitcnt lgkmcnt(0)
	v_pk_mul_f32 v[12:13], v[12:13], v[40:41]
	v_pk_mul_f32 v[14:15], v[14:15], v[42:43]
	ds_read_b128 v[40:43], v101 offset:39424
	s_waitcnt lgkmcnt(0)
	v_mfma_f32_16x16x32_bf16 v[12:15], v[40:43], v[36:39], v[12:15]
	ds_read_b128 v[40:43], v101 offset:39488
	s_waitcnt lgkmcnt(0)
	v_mfma_f32_16x16x32_bf16 v[12:15], v[40:43], v[32:35], v[12:15]
	ds_read_b128 v[40:43], v86 offset:62656
	s_waitcnt lgkmcnt(0)
	v_pk_mul_f32 v[8:9], v[8:9], v[40:41]
	v_pk_mul_f32 v[10:11], v[10:11], v[42:43]
	ds_read_b128 v[40:43], v101 offset:41728
	s_waitcnt lgkmcnt(0)
	v_mfma_f32_16x16x32_bf16 v[8:11], v[40:43], v[36:39], v[8:11]
	ds_read_b128 v[40:43], v101 offset:41792
	s_waitcnt lgkmcnt(0)
	v_mfma_f32_16x16x32_bf16 v[8:11], v[40:43], v[32:35], v[8:11]
	ds_read_b128 v[40:43], v86 offset:62720
	s_waitcnt lgkmcnt(0)
	v_pk_mul_f32 v[20:21], v[20:21], v[40:41]
	v_pk_mul_f32 v[22:23], v[22:23], v[42:43]
	ds_read_b128 v[40:43], v101 offset:44032
	s_waitcnt lgkmcnt(0)
	v_mfma_f32_16x16x32_bf16 v[20:23], v[40:43], v[36:39], v[20:23]
	ds_read_b128 v[40:43], v101 offset:44096
	s_waitcnt lgkmcnt(0)
	v_mfma_f32_16x16x32_bf16 v[20:23], v[40:43], v[32:35], v[20:23]
	ds_read_b128 v[40:43], v86 offset:62784
	s_waitcnt lgkmcnt(0)
	v_pk_mul_f32 v[16:17], v[16:17], v[40:41]
	v_pk_mul_f32 v[18:19], v[18:19], v[42:43]
	ds_read_b128 v[40:43], v101 offset:46336
	s_waitcnt lgkmcnt(0)
	v_mfma_f32_16x16x32_bf16 v[16:19], v[40:43], v[36:39], v[16:19]
	ds_read_b128 v[40:43], v101 offset:46400
	s_waitcnt lgkmcnt(0)
	v_mfma_f32_16x16x32_bf16 v[16:19], v[40:43], v[32:35], v[16:19]
	ds_read_b128 v[40:43], v86 offset:62848
	s_waitcnt lgkmcnt(0)
	v_pk_mul_f32 v[24:25], v[24:25], v[40:41]
	v_pk_mul_f32 v[26:27], v[26:27], v[42:43]
	ds_read_b128 v[40:43], v101 offset:48640
	s_waitcnt lgkmcnt(0)
	v_mfma_f32_16x16x32_bf16 v[24:27], v[40:43], v[36:39], v[24:27]
	ds_read_b128 v[40:43], v101 offset:48704
	s_waitcnt lgkmcnt(0)
	v_mfma_f32_16x16x32_bf16 v[24:27], v[40:43], v[32:35], v[24:27]
	ds_read_b128 v[40:43], v86 offset:62912
	s_waitcnt lgkmcnt(0)
	v_pk_mul_f32 v[28:29], v[28:29], v[40:41]
	v_pk_mul_f32 v[30:31], v[30:31], v[42:43]
	ds_read_b128 v[40:43], v101 offset:50944
	s_waitcnt lgkmcnt(0)
	v_mfma_f32_16x16x32_bf16 v[28:31], v[40:43], v[36:39], v[28:31]
	ds_read_b128 v[36:39], v101 offset:51008
	s_waitcnt lgkmcnt(0)
	s_barrier
	v_mfma_f32_16x16x32_bf16 v[28:31], v[36:39], v[32:35], v[28:31]
	s_cbranch_scc1 .LBB0_952
.LBB0_1003:
	s_waitcnt vmcnt(4)
; DI float f16lo(unsigned u) { return (float)__builtin_bit_cast(h16x2, u)[0]; }
; DI float f16hi(unsigned u) { return (float)__builtin_bit_cast(h16x2, u)[1]; }
; DI unsigned pk_bf16(float lo, float hi) { f32x2 v = {lo, hi}; return __builtin_bit_cast(unsigned, __builtin_convertvector(v, bf16x2_t)); }
; DI void hgrn_item(const Params& p, const int ch) {
;     ...
;     float lf0[8], lf1[8], gk0[8], gk1[8];
;     float run0 = 0.f, run1 = 0.f;
; #pragma unroll
;     for (int j = 0; j < 8; ++j) {
;       const float f0 = f16lo(fraw[j]), f1 = f16hi(fraw[j]);
;       gk0[j] = 1.f - __expf(f0); gk1[j] = 1.f - __expf(f1);
;       run0 += f0; run1 += f1; lf0[j] = run0; lf1[j] = run1;
;     }
;     { float2 rr; rr.x = run0; rr.y = run1; *(float2*)(shm_raw + HG_SEG + (seg * 128 + k0) * 4) = rr; }
;     __syncthreads();
;     float off0 = 0.f, off1 = 0.f, bl0 = 0.f, bl1 = 0.f;
; #pragma unroll
;     for (int s2 = 0; s2 < 8; ++s2) {
;       const float2 tt = *(const float2*)(shm_raw + HG_SEG + (s2 * 128 + k0) * 4);
;       bl0 += tt.x; bl1 += tt.y;
;       const bool before = dir ? (s2 > seg) : (s2 < seg);
;       off0 += before ? tt.x : 0.f; off1 += before ? tt.y : 0.f;
;     }
;     float ks0[8], ks1[8];
; #pragma unroll
;     for (int j = 0; j < 8; ++j) {
;       const float b0 = lf0[j] + off0, b1 = lf1[j] + off1;
;       const float q0 = __uint_as_float(qraw[j] << 16), q1 = __uint_as_float(qraw[j] & 0xffff0000u);
;       const int c = cstart + j * cstep;
;       *(unsigned*)(shm_raw + HG_QT + c * 272 + k0 * 2) = pk_bf16(q0 * __expf(b0), q1 * __expf(b1));
;       *(unsigned*)(shm_raw + HG_KT + c * 272 + k0 * 2) = pk_bf16(gk0[j] * __expf(-b0), gk1[j] * __expf(-b1));
;       ks0[j] = gk0[j] * __expf(bl0 - b0); ks1[j] = gk1[j] * __expf(bl1 - b1);
.Lhg_after_wait:
	v_cvt_f32_f16_e32 v32, v74
	v_cvt_f32_f16_sdwa v33, v74 dst_sel:DWORD dst_unused:UNUSED_PAD src0_sel:WORD_1
	v_cvt_f32_f16_e32 v34, v76
	v_cvt_f32_f16_e32 v68, v94
	v_mul_f32_e32 v35, 0x3fb8aa3b, v32
	v_exp_f32_e32 v40, v35
	v_cvt_f32_f16_sdwa v35, v76 dst_sel:DWORD dst_unused:UNUSED_PAD src0_sel:WORD_1
	v_pk_add_f32 v[48:49], v[32:33], 0 op_sel_hi:[1,0]
	v_mul_f32_e32 v32, 0x3fb8aa3b, v34
	v_mul_f32_e32 v36, 0x3fb8aa3b, v33
	v_exp_f32_e32 v50, v32
	v_mul_f32_e32 v33, 0x3fb8aa3b, v35
	v_cvt_f32_f16_e32 v32, v78
	v_exp_f32_e32 v51, v33
	v_cvt_f32_f16_sdwa v33, v78 dst_sel:DWORD dst_unused:UNUSED_PAD src0_sel:WORD_1
	v_pk_add_f32 v[46:47], v[48:49], v[34:35]
	v_mul_f32_e32 v34, 0x3fb8aa3b, v32
	v_exp_f32_e32 v52, v34
	v_mul_f32_e32 v35, 0x3fb8aa3b, v33
	v_cvt_f32_f16_e32 v34, v80
	v_exp_f32_e32 v53, v35
	v_cvt_f32_f16_sdwa v35, v80 dst_sel:DWORD dst_unused:UNUSED_PAD src0_sel:WORD_1
	v_pk_add_f32 v[44:45], v[46:47], v[32:33]
	v_mul_f32_e32 v32, 0x3fb8aa3b, v34
	v_exp_f32_e32 v54, v32
	v_mul_f32_e32 v33, 0x3fb8aa3b, v35
	v_cvt_f32_f16_e32 v32, v88
	v_exp_f32_e32 v55, v33
	v_cvt_f32_f16_sdwa v33, v88 dst_sel:DWORD dst_unused:UNUSED_PAD src0_sel:WORD_1
	v_pk_add_f32 v[42:43], v[44:45], v[34:35]
	v_mul_f32_e32 v34, 0x3fb8aa3b, v32
	v_exp_f32_e32 v66, v34
	v_mul_f32_e32 v35, 0x3fb8aa3b, v33
	v_cvt_f32_f16_e32 v34, v90
	v_exp_f32_e32 v67, v35
	v_cvt_f32_f16_sdwa v35, v90 dst_sel:DWORD dst_unused:UNUSED_PAD src0_sel:WORD_1
	v_pk_add_f32 v[38:39], v[42:43], v[32:33]
	v_mul_f32_e32 v32, 0x3fb8aa3b, v34
	v_exp_f32_e32 v116, v32
	v_mul_f32_e32 v33, 0x3fb8aa3b, v35
	v_cvt_f32_f16_e32 v32, v92
	v_exp_f32_e32 v117, v33
	v_cvt_f32_f16_sdwa v33, v92 dst_sel:DWORD dst_unused:UNUSED_PAD src0_sel:WORD_1
	v_cvt_f32_f16_sdwa v69, v94 dst_sel:DWORD dst_unused:UNUSED_PAD src0_sel:WORD_1
	v_exp_f32_e32 v41, v36
	v_pk_add_f32 v[36:37], v[38:39], v[34:35]
	v_mul_f32_e32 v34, 0x3fb8aa3b, v32
	v_exp_f32_e32 v118, v34
	v_mul_f32_e32 v34, 0x3fb8aa3b, v33
	v_exp_f32_e32 v119, v34
	v_pk_add_f32 v[34:35], v[36:37], v[32:33]
	v_add_u32_e32 v33, s70, v72
	v_pk_add_f32 v[120:121], v[34:35], v[68:69]
	ds_write_b64 v33, v[120:121] offset:62976
	s_waitcnt lgkmcnt(0)
	s_barrier
	ds_read2st64_b64 v[104:107], v81 offset0:123 offset1:124
	ds_read_b64 v[122:123], v81 offset:65024
	ds_read2st64_b64 v[108:111], v81 offset0:125 offset1:126
	ds_read2st64_b64 v[112:115], v82 offset0:5 offset1:6
	ds_read_b64 v[136:137], v82 offset:3584
	v_pk_add_f32 v[152:153], v[40:41], 1.0 op_sel_hi:[1,0] neg_lo:[1,0] neg_hi:[1,0]
	v_pk_add_f32 v[156:157], v[50:51], 1.0 op_sel_hi:[1,0] neg_lo:[1,0] neg_hi:[1,0]
	v_pk_add_f32 v[50:51], v[118:119], 1.0 op_sel_hi:[1,0] neg_lo:[1,0] neg_hi:[1,0]
	s_waitcnt lgkmcnt(4)
	v_add_f32_e32 v40, 0, v104
	v_add_f32_e32 v118, 0, v105
	v_cndmask_b32_e64 v124, 0, v106, s[8:9]
	v_cndmask_b32_e64 v126, 0, v107, s[8:9]
	v_cndmask_b32_e64 v41, 0, v40, s[6:7]
	v_cndmask_b32_e64 v105, 0, v118, s[6:7]
	s_waitcnt lgkmcnt(2)
	v_cndmask_b32_e64 v125, 0, v108, s[10:11]
	v_cndmask_b32_e64 v127, 0, v109, s[10:11]
	v_add_f32_e32 v41, v41, v124
	v_mov_b32_e32 v124, v106
	v_add_f32_e32 v119, v105, v126
	v_mov_b32_e32 v126, v107
	v_cndmask_b32_e64 v129, 0, v110, s[12:13]
	v_cndmask_b32_e64 v131, 0, v111, s[12:13]
	v_pk_add_f32 v[40:41], v[40:41], v[124:125]
	v_mov_b32_e32 v128, v108
	v_pk_add_f32 v[118:119], v[118:119], v[126:127]
	v_mov_b32_e32 v130, v109
	v_cndmask_b32_e64 v133, 0, v122, s[14:15]
	v_cndmask_b32_e64 v135, 0, v123, s[14:15]
	v_pk_add_f32 v[40:41], v[40:41], v[128:129]
	v_mov_b32_e32 v132, v110
	v_pk_add_f32 v[118:119], v[118:119], v[130:131]
	v_mov_b32_e32 v134, v111
	s_waitcnt lgkmcnt(1)
	v_cndmask_b32_e64 v139, 0, v112, s[16:17]
	v_cndmask_b32_e64 v141, 0, v113, s[16:17]
	v_pk_add_f32 v[40:41], v[40:41], v[132:133]
	v_mov_b32_e32 v138, v122
	v_pk_add_f32 v[118:119], v[118:119], v[134:135]
	v_mov_b32_e32 v140, v123
	v_cndmask_b32_e64 v143, 0, v114, s[18:19]
	v_cndmask_b32_e64 v145, 0, v115, s[18:19]
	v_pk_add_f32 v[40:41], v[40:41], v[138:139]
	v_mov_b32_e32 v142, v112
	v_pk_add_f32 v[118:119], v[118:119], v[140:141]
	v_mov_b32_e32 v144, v113
	s_waitcnt lgkmcnt(0)
	v_cndmask_b32_e64 v147, 0, v136, s[20:21]
	v_cndmask_b32_e64 v149, 0, v137, s[20:21]
	v_pk_add_f32 v[40:41], v[40:41], v[142:143]
	v_mov_b32_e32 v146, v114
	v_pk_add_f32 v[118:119], v[118:119], v[144:145]
	v_mov_b32_e32 v148, v115
	v_pk_add_f32 v[164:165], v[54:55], 1.0 op_sel_hi:[1,0] neg_lo:[1,0] neg_hi:[1,0]
	v_pk_add_f32 v[54:55], v[116:117], 1.0 op_sel_hi:[1,0] neg_lo:[1,0] neg_hi:[1,0]
	v_pk_add_f32 v[116:117], v[40:41], v[146:147]
	v_pk_add_f32 v[118:119], v[118:119], v[148:149]
	v_add_f32_e32 v104, v48, v117
	v_mov_b32_e32 v40, v136
	v_mov_b32_e32 v41, v120
	v_add_f32_e32 v107, v49, v119
	v_mul_f32_e32 v48, 0x3fb8aa3b, v104
	v_pk_add_f32 v[40:41], v[116:117], v[40:41]
	v_mul_f32_e32 v49, 0x3fb8aa3b, v107
	v_sub_f32_e32 v106, v40, v104
	v_exp_f32_e32 v48, v48
	v_mul_f32_e32 v104, 0xbfb8aa3b, v104
	v_exp_f32_e32 v49, v49
	v_mul_f32_e32 v105, 0xbfb8aa3b, v107
	v_mul_f32_e32 v106, 0x3fb8aa3b, v106
	v_exp_f32_e32 v104, v104
	v_exp_f32_e32 v105, v105
	v_exp_f32_e32 v106, v106
	v_lshlrev_b32_e32 v150, 16, v75
	v_and_b32_e32 v151, 0xffff0000, v75
	v_pk_mul_f32 v[48:49], v[48:49], v[150:151]
	s_mul_i32 s40, s78, 0x110
	v_cvt_pk_bf16_f32 v109, v48, v49
	v_pk_mul_f32 v[48:49], v[152:153], v[104:105]
	v_mul_f32_e32 v122, v152, v106
	v_add_f32_e32 v106, v46, v117
	v_add_u32_e32 v111, s40, v83
	v_cvt_pk_bf16_f32 v48, v48, v49
	v_mov_b32_e32 v120, v137
	v_add_f32_e32 v105, v47, v119
	v_mul_f32_e32 v46, 0x3fb8aa3b, v106
	ds_write2st64_b32 v111, v109, v48 offset1:68
	v_pk_add_f32 v[48:49], v[118:119], v[120:121]
; DI unsigned pk_bf16(float lo, float hi) { f32x2 v = {lo, hi}; return __builtin_bit_cast(unsigned, __builtin_convertvector(v, bf16x2_t)); }
; DI void hgrn_item(const Params& p, const int ch) {
;     ...
;     float ks0[8], ks1[8];
; #pragma unroll
;     for (int j = 0; j < 8; ++j) {
;       const float b0 = lf0[j] + off0, b1 = lf1[j] + off1;
;       const float q0 = __uint_as_float(qraw[j] << 16), q1 = __uint_as_float(qraw[j] & 0xffff0000u);
;       const int c = cstart + j * cstep;
;       *(unsigned*)(shm_raw + HG_QT + c * 272 + k0 * 2) = pk_bf16(q0 * __expf(b0), q1 * __expf(b1));
;       *(unsigned*)(shm_raw + HG_KT + c * 272 + k0 * 2) = pk_bf16(gk0[j] * __expf(-b0), gk1[j] * __expf(-b1));
;       ks0[j] = gk0[j] * __expf(bl0 - b0); ks1[j] = gk1[j] * __expf(bl1 - b1);
;     }
	v_mul_f32_e32 v47, 0x3fb8aa3b, v105
	v_sub_f32_e32 v108, v40, v106
	v_exp_f32_e32 v46, v46
	v_mul_f32_e32 v106, 0xbfb8aa3b, v106
	v_sub_f32_e32 v104, v48, v107
	v_exp_f32_e32 v47, v47
	v_mul_f32_e32 v107, 0xbfb8aa3b, v105
	v_mul_f32_e32 v108, 0x3fb8aa3b, v108
	v_exp_f32_e32 v106, v106
	v_exp_f32_e32 v107, v107
	v_exp_f32_e32 v108, v108
	v_lshlrev_b32_e32 v154, 16, v77
	v_and_b32_e32 v155, 0xffff0000, v77
	v_pk_mul_f32 v[46:47], v[46:47], v[154:155]
	v_mul_f32_e32 v124, v156, v108
	v_cvt_pk_bf16_f32 v109, v46, v47
	v_pk_mul_f32 v[46:47], v[156:157], v[106:107]
	v_add_f32_e32 v108, v44, v117
	v_cvt_pk_bf16_f32 v46, v46, v47
	v_add_f32_e32 v47, v45, v119
	v_mul_f32_e32 v44, 0x3fb8aa3b, v108
	v_add_u32_e32 v111, s3, v83
	v_mul_f32_e32 v45, 0x3fb8aa3b, v47
	v_sub_f32_e32 v110, v40, v108
	v_exp_f32_e32 v44, v44
	v_mul_f32_e32 v108, 0xbfb8aa3b, v108
	ds_write2st64_b32 v111, v109, v46 offset1:68
	v_sub_f32_e32 v46, v48, v105
	v_exp_f32_e32 v45, v45
	v_mul_f32_e32 v105, 0xbfb8aa3b, v47
	v_mul_f32_e32 v110, 0x3fb8aa3b, v110
	v_exp_f32_e32 v108, v108
	v_exp_f32_e32 v109, v105
	v_exp_f32_e32 v110, v110
	v_lshlrev_b32_e32 v158, 16, v79
	v_and_b32_e32 v159, 0xffff0000, v79
	v_pk_add_f32 v[160:161], v[52:53], 1.0 op_sel_hi:[1,0] neg_lo:[1,0] neg_hi:[1,0]
	v_pk_mul_f32 v[44:45], v[44:45], v[158:159]
	v_mul_f32_e32 v125, v160, v110
	v_cvt_pk_bf16_f32 v105, v44, v45
	v_pk_mul_f32 v[44:45], v[160:161], v[108:109]
	v_add_f32_e32 v110, v42, v117
	v_cvt_pk_bf16_f32 v44, v44, v45
	v_add_f32_e32 v45, v43, v119
	v_mul_f32_e32 v42, 0x3fb8aa3b, v110
	v_add_u32_e32 v106, s33, v83
	v_mul_f32_e32 v43, 0x3fb8aa3b, v45
	v_sub_f32_e32 v112, v40, v110
	v_exp_f32_e32 v42, v42
	v_mul_f32_e32 v110, 0xbfb8aa3b, v110
	ds_write2st64_b32 v106, v105, v44 offset1:68
	v_sub_f32_e32 v44, v48, v47
	v_exp_f32_e32 v43, v43
	v_mul_f32_e32 v47, 0xbfb8aa3b, v45
	v_mul_f32_e32 v112, 0x3fb8aa3b, v112
	v_exp_f32_e32 v110, v110
	v_exp_f32_e32 v111, v47
	v_exp_f32_e32 v112, v112
	v_lshlrev_b32_e32 v162, 16, v87
	v_and_b32_e32 v163, 0xffff0000, v87
	v_pk_mul_f32 v[42:43], v[42:43], v[162:163]
	v_mul_f32_e32 v128, v164, v112
	v_cvt_pk_bf16_f32 v47, v42, v43
	v_pk_mul_f32 v[42:43], v[164:165], v[110:111]
	v_add_f32_e32 v112, v38, v117
	v_cvt_pk_bf16_f32 v42, v42, v43
	v_add_f32_e32 v43, v39, v119
	v_mul_f32_e32 v38, 0x3fb8aa3b, v112
	v_add_u32_e32 v105, s49, v83
	v_mul_f32_e32 v39, 0x3fb8aa3b, v43
	v_sub_f32_e32 v114, v40, v112
	v_exp_f32_e32 v38, v38
	v_mul_f32_e32 v112, 0xbfb8aa3b, v112
	ds_write2st64_b32 v105, v47, v42 offset1:68
	v_sub_f32_e32 v42, v48, v45
	v_exp_f32_e32 v39, v39
	v_mul_f32_e32 v45, 0xbfb8aa3b, v43
	v_mul_f32_e32 v114, 0x3fb8aa3b, v114
	v_exp_f32_e32 v112, v112
	v_exp_f32_e32 v113, v45
	v_exp_f32_e32 v114, v114
	v_lshlrev_b32_e32 v70, 16, v89
	v_and_b32_e32 v71, 0xffff0000, v89
	v_mul_f32_e32 v32, 0x3fb8aa3b, v68
	v_mul_f32_e32 v33, 0x3fb8aa3b, v69
	v_pk_add_f32 v[68:69], v[66:67], 1.0 op_sel_hi:[1,0] neg_lo:[1,0] neg_hi:[1,0]
	v_pk_mul_f32 v[38:39], v[38:39], v[70:71]
	v_mul_f32_e32 v129, v68, v114
	v_cvt_pk_bf16_f32 v45, v38, v39
	v_pk_mul_f32 v[38:39], v[68:69], v[112:113]
	v_add_f32_e32 v114, v36, v117
	v_cvt_pk_bf16_f32 v38, v38, v39
	v_add_f32_e32 v39, v37, v119
	v_mul_f32_e32 v36, 0x3fb8aa3b, v114
	v_add_u32_e32 v47, s52, v83
	v_mul_f32_e32 v37, 0x3fb8aa3b, v39
	v_sub_f32_e32 v116, v40, v114
	v_exp_f32_e32 v36, v36
	v_mul_f32_e32 v114, 0xbfb8aa3b, v114
	ds_write2st64_b32 v47, v45, v38 offset1:68
	v_sub_f32_e32 v38, v48, v43
	v_exp_f32_e32 v37, v37
	v_mul_f32_e32 v43, 0xbfb8aa3b, v39
	v_exp_f32_e32 v114, v114
	v_exp_f32_e32 v115, v43
	v_lshlrev_b32_e32 v66, 16, v91
	v_and_b32_e32 v67, 0xffff0000, v91
	v_mul_f32_e32 v116, 0x3fb8aa3b, v116
	v_exp_f32_e32 v116, v116
	v_pk_mul_f32 v[36:37], v[36:37], v[66:67]
	v_add_u32_e32 v45, s90, v83
; DI unsigned pk_bf16(float lo, float hi) { f32x2 v = {lo, hi}; return __builtin_bit_cast(unsigned, __builtin_convertvector(v, bf16x2_t)); }
; DI void hgrn_item(const Params& p, const int ch) {
;     ...
;     float ks0[8], ks1[8];
; #pragma unroll
;     for (int j = 0; j < 8; ++j) {
;       const float b0 = lf0[j] + off0, b1 = lf1[j] + off1;
;       const float q0 = __uint_as_float(qraw[j] << 16), q1 = __uint_as_float(qraw[j] & 0xffff0000u);
;       const int c = cstart + j * cstep;
;       *(unsigned*)(shm_raw + HG_QT + c * 272 + k0 * 2) = pk_bf16(q0 * __expf(b0), q1 * __expf(b1));
;       *(unsigned*)(shm_raw + HG_KT + c * 272 + k0 * 2) = pk_bf16(gk0[j] * __expf(-b0), gk1[j] * __expf(-b1));
;       ks0[j] = gk0[j] * __expf(bl0 - b0); ks1[j] = gk1[j] * __expf(bl1 - b1);
;     }
;     {
;       uint4 w0, w1;
;       w0.x = pk_bf16(dir ? ks0[7] : ks0[0], dir ? ks0[6] : ks0[1]); w0.y = pk_bf16(dir ? ks0[5] : ks0[2], dir ? ks0[4] : ks0[3]);
;       w0.z = pk_bf16(dir ? ks0[3] : ks0[4], dir ? ks0[2] : ks0[5]); w0.w = pk_bf16(dir ? ks0[1] : ks0[6], dir ? ks0[0] : ks0[7]);
;       w1.x = pk_bf16(dir ? ks1[7] : ks1[0], dir ? ks1[6] : ks1[1]); w1.y = pk_bf16(dir ? ks1[5] : ks1[2], dir ? ks1[4] : ks1[3]);
;       w1.z = pk_bf16(dir ? ks1[3] : ks1[4], dir ? ks1[2] : ks1[5]); w1.w = pk_bf16(dir ? ks1[1] : ks1[6], dir ? ks1[0] : ks1[7]);
;       *(uint4*)(shm_raw + HG_KST + k0 * 144 + seg * 16) = w0;
;       *(uint4*)(shm_raw + HG_KST + (k0 + 1) * 144 + seg * 16) = w1;
;     }
;     if (seg == 0) { float2 dd; dd.x = __expf(bl0); dd.y = __expf(bl1); *(float2*)(shm_raw + HG_DEC + k0 * 4) = dd; }
	v_cvt_pk_bf16_f32 v43, v36, v37
	v_pk_mul_f32 v[36:37], v[54:55], v[114:115]
	v_add_f32_e32 v117, v34, v117
	v_cvt_pk_bf16_f32 v36, v36, v37
	ds_write2st64_b32 v45, v43, v36 offset1:68
	v_sub_f32_e32 v36, v48, v39
	v_mul_f32_e32 v132, v54, v116
	v_mul_f32_e32 v34, 0x3fb8aa3b, v117
	v_mul_f32_e32 v116, 0xbfb8aa3b, v117
	v_sub_f32_e32 v117, v40, v117
	v_mul_f32_e32 v36, 0x3fb8aa3b, v36
	v_mul_f32_e32 v117, 0x3fb8aa3b, v117
	v_exp_f32_e32 v36, v36
	v_exp_f32_e32 v117, v117
	v_add_f32_e32 v37, v35, v119
	v_mul_f32_e32 v35, 0x3fb8aa3b, v37
	v_exp_f32_e32 v34, v34
	v_exp_f32_e32 v35, v35
	v_mul_f32_e32 v39, v55, v36
	v_mul_f32_e32 v36, 0xbfb8aa3b, v37
	v_exp_f32_e32 v116, v116
	v_mul_f32_e32 v123, v50, v117
	v_exp_f32_e32 v117, v36
	v_lshlrev_b32_e32 v52, 16, v93
	v_and_b32_e32 v53, 0xffff0000, v93
	v_pk_mul_f32 v[34:35], v[34:35], v[52:53]
	v_add_u32_e32 v43, s79, v83
	v_cvt_pk_bf16_f32 v36, v34, v35
	v_pk_mul_f32 v[34:35], v[50:51], v[116:117]
	v_exp_f32_e32 v32, v32
	v_cvt_pk_bf16_f32 v34, v34, v35
	ds_write2st64_b32 v43, v36, v34 offset1:68
	v_sub_f32_e32 v34, v48, v37
	v_mul_f32_e32 v34, 0x3fb8aa3b, v34
	v_exp_f32_e32 v36, v34
	v_mul_f32_e32 v34, 0x3fb8aa3b, v41
	v_mul_f32_e32 v35, 0x3fb8aa3b, v49
	v_exp_f32_e32 v34, v34
	v_exp_f32_e32 v35, v35
	v_mul_f32_e32 v43, v51, v36
	v_lshlrev_b32_e32 v36, 16, v103
	v_and_b32_e32 v37, 0xffff0000, v103
	v_exp_f32_e32 v33, v33
	v_pk_mul_f32 v[34:35], v[34:35], v[36:37]
	v_mul_f32_e32 v36, 0xbfb8aa3b, v41
	v_mul_f32_e32 v37, 0xbfb8aa3b, v49
	v_exp_f32_e32 v36, v36
	v_exp_f32_e32 v37, v37
	v_pk_add_f32 v[32:33], v[32:33], 1.0 op_sel_hi:[1,0] neg_lo:[1,0] neg_hi:[1,0]
	v_cvt_pk_bf16_f32 v45, v34, v35
	v_mul_f32_e32 v104, 0x3fb8aa3b, v104
	v_pk_mul_f32 v[34:35], v[32:33], v[36:37]
	v_sub_f32_e32 v36, v40, v41
	v_mul_f32_e32 v36, 0x3fb8aa3b, v36
	v_sub_f32_e32 v37, v48, v49
	v_exp_f32_e32 v36, v36
	v_mul_f32_e32 v37, 0x3fb8aa3b, v37
	v_exp_f32_e32 v37, v37
	v_mul_f32_e32 v46, 0x3fb8aa3b, v46
	v_exp_f32_e32 v104, v104
	v_exp_f32_e32 v46, v46
	v_mul_f32_e32 v44, 0x3fb8aa3b, v44
	v_mul_f32_e32 v42, 0x3fb8aa3b, v42
	v_mul_f32_e32 v38, 0x3fb8aa3b, v38
	v_cvt_pk_bf16_f32 v34, v34, v35
	v_mul_f32_e32 v35, v32, v36
	v_exp_f32_e32 v44, v44
	v_exp_f32_e32 v42, v42
	v_exp_f32_e32 v38, v38
	v_add_u32_e32 v47, s44, v83
	v_mul_f32_e32 v41, v33, v37
	v_cndmask_b32_e64 v32, v35, v122, s[4:5]
	v_cndmask_b32_e64 v33, v123, v124, s[4:5]
	ds_write2st64_b32 v47, v45, v34 offset1:68
	v_cvt_pk_bf16_f32 v32, v32, v33
	v_cndmask_b32_e64 v33, v132, v125, s[4:5]
	v_cndmask_b32_e64 v34, v129, v128, s[4:5]
	v_cvt_pk_bf16_f32 v33, v33, v34
	v_cndmask_b32_e64 v34, v128, v129, s[4:5]
	v_cndmask_b32_e64 v36, v125, v132, s[4:5]
	v_mul_f32_e32 v104, v153, v104
	v_mul_f32_e32 v46, v157, v46
	v_cvt_pk_bf16_f32 v34, v34, v36
	v_cndmask_b32_e64 v36, v124, v123, s[4:5]
	v_cndmask_b32_e64 v35, v122, v35, s[4:5]
	v_mul_f32_e32 v44, v161, v44
	v_mul_f32_e32 v42, v165, v42
	v_mul_f32_e32 v38, v69, v38
	v_cvt_pk_bf16_f32 v35, v36, v35
	v_cndmask_b32_e64 v36, v41, v104, s[4:5]
	v_cndmask_b32_e64 v37, v43, v46, s[4:5]
	v_cvt_pk_bf16_f32 v36, v36, v37
	v_cndmask_b32_e64 v37, v39, v44, s[4:5]
	v_cndmask_b32_e64 v45, v38, v42, s[4:5]
	v_cndmask_b32_e64 v38, v42, v38, s[4:5]
	v_cndmask_b32_e64 v39, v44, v39, s[4:5]
	v_cvt_pk_bf16_f32 v38, v38, v39
	v_cndmask_b32_e64 v39, v46, v43, s[4:5]
	v_cndmask_b32_e64 v41, v104, v41, s[4:5]
	v_cvt_pk_bf16_f32 v37, v37, v45
	v_cvt_pk_bf16_f32 v39, v39, v41
	v_add_u32_e32 v41, s0, v84
	s_andn2_b64 vcc, exec, s[64:65]
	ds_write_b128 v41, v[32:35] offset:34816
	ds_write_b128 v41, v[36:39] offset:34960
	s_cbranch_vccnz .LBB0_1005
	v_mul_f32_e32 v32, 0x3fb8aa3b, v40
	v_mul_f32_e32 v33, 0x3fb8aa3b, v48
	v_exp_f32_e32 v32, v32
	v_exp_f32_e32 v33, v33
	ds_write_b64 v97, v[32:33] offset:62464
